# sc1 on the attention output stores so their write-back happens during the compute-bound attention phase instead of the bandwidth-bound elementwise phase
# baseline (speedup 1.0000x reference)
; #define LAS __attribute__((address_space(3)))
; __device__ __forceinline__ int crow(int r, int hi) { return (r & 3) + 8 * (r >> 2) + 4 * hi; }
; __device__ __forceinline__ unsigned cvtpk_s(float lo, float hi) { f32x2 v = {lo, hi}; typedef __bf16 bf16x2_t __attribute__((ext_vector_type(2))); bf16x2_t b = __builtin_convertvector(v, bf16x2_t); return __builtin_bit_cast(unsigned, b); }
; __device__ __forceinline__ void attn_unit(int b, int h, int qb, const bf16* Q, const bf16* __restrict__ Kn, const bf16* __restrict__ Kpe, const bf16* __restrict__ V, bf16* O, float* ASS, LAS char* shm) {
;     ...
;     { auto rr = __builtin_amdgcn_permlane32_swap(__float_as_uint(l_run), __float_as_uint(l_run), false, false); l_run = __uint_as_float(rr[0]) + __uint_as_float(rr[1]); }
;     if (hi == 0) wsf[32 + r32] = l_run; asm volatile("s_waitcnt lgkmcnt(0)" ::: "memory");
;     float rli[16];
; #pragma unroll
;     for (int r = 0; r < 16; ++r) rli[r] = __builtin_amdgcn_rcpf(wsf[32 + crow(r, hi)]);
;     bf16* Ow = O + (rowbase + q0 + wid * QBLK) * OP + h * 64;
;     { LAS unsigned short* stg = (LAS unsigned short*)(shm + LDS_OST) + wid * 2048;
; #pragma unroll
;       for (int r = 0; r < 16; ++r) { const int orow = crow(r, hi);
; #pragma unroll
;           for (int d0 = 0; d0 < 2; ++d0) stg[orow * 64 + d0 * 32 + r32] = (unsigned short)(cvtpk_s(o[d0][r] * rli[r], 0.f) & 0xffffu); }
;       asm volatile("s_waitcnt lgkmcnt(0)" ::: "memory");
; #pragma unroll
;       for (int i = 0; i < 4; ++i) { const int row = i * 8 + (lane >> 3), ch = lane & 7; const u32x4 v = *(const LAS u32x4*)(stg + row * 64 + ch * 8); *(u32x4*)(Ow + (long)row * OP + ch * 8) = v;
;           float sq = 0.f;
; #pragma unroll
;           for (int k = 0; k < 4; ++k) { const float a = __uint_as_float(v[k] << 16), bq = __uint_as_float(v[k] & 0xffff0000u); sq += a * a + bq * bq; }
;           sq += __shfl_xor(sq, 1); sq += __shfl_xor(sq, 2); sq += __shfl_xor(sq, 4);
;           if (ch == 0) ASS[(rowbase + q0 + wid * QBLK + row) * 8 + h] = sq; } }
.Lat_u1t_skip:
	s_nop 7
	s_nop 7
	v_mov_b32_e32 v212, v128
	s_nop 1
	v_permlane32_swap_b32_e32 v128, v212
	s_nop 0
	v_add_f32_e32 v128, v128, v212
	v_rcp_f32_e32 v212, v128
	v_mov_b32_e32 v213, 0
	v_mul_f32_e32 v230, v16, v212
	v_mul_f32_e32 v231, v17, v212
	v_mul_f32_e32 v232, v18, v212
	v_mul_f32_e32 v233, v19, v212
	v_cvt_pk_bf16_f32 v196, v230, v231
	v_cvt_pk_bf16_f32 v197, v232, v233
	v_mul_f32_e32 v230, v20, v212
	v_mul_f32_e32 v231, v21, v212
	v_mul_f32_e32 v232, v22, v212
	v_mul_f32_e32 v233, v23, v212
	v_cvt_pk_bf16_f32 v198, v230, v231
	v_cvt_pk_bf16_f32 v199, v232, v233
	v_mul_f32_e32 v230, v24, v212
	v_mul_f32_e32 v231, v25, v212
	v_mul_f32_e32 v232, v26, v212
	v_mul_f32_e32 v233, v27, v212
	v_cvt_pk_bf16_f32 v200, v230, v231
	v_cvt_pk_bf16_f32 v201, v232, v233
	v_mul_f32_e32 v230, v28, v212
	v_mul_f32_e32 v231, v29, v212
	v_mul_f32_e32 v232, v30, v212
	v_mul_f32_e32 v233, v31, v212
	v_cvt_pk_bf16_f32 v202, v230, v231
	v_cvt_pk_bf16_f32 v203, v232, v233
	v_mul_f32_e32 v230, v32, v212
	v_mul_f32_e32 v231, v33, v212
	v_mul_f32_e32 v232, v34, v212
	v_mul_f32_e32 v233, v35, v212
	v_cvt_pk_bf16_f32 v204, v230, v231
	v_cvt_pk_bf16_f32 v205, v232, v233
	v_mul_f32_e32 v230, v36, v212
	v_mul_f32_e32 v231, v37, v212
	v_mul_f32_e32 v232, v38, v212
	v_mul_f32_e32 v233, v39, v212
	v_cvt_pk_bf16_f32 v206, v230, v231
	v_cvt_pk_bf16_f32 v207, v232, v233
	v_mul_f32_e32 v230, v40, v212
	v_mul_f32_e32 v231, v41, v212
	v_mul_f32_e32 v232, v42, v212
	v_mul_f32_e32 v233, v43, v212
	v_cvt_pk_bf16_f32 v208, v230, v231
	v_cvt_pk_bf16_f32 v209, v232, v233
	v_mul_f32_e32 v230, v44, v212
	v_mul_f32_e32 v231, v45, v212
	v_mul_f32_e32 v232, v46, v212
	v_mul_f32_e32 v233, v47, v212
	v_cvt_pk_bf16_f32 v210, v230, v231
	v_cvt_pk_bf16_f32 v211, v232, v233
	s_nop 1
	v_permlane32_swap_b32_e32 v196, v198
	v_permlane32_swap_b32_e32 v197, v199
	v_permlane32_swap_b32_e32 v200, v202
	v_permlane32_swap_b32_e32 v201, v203
	v_permlane32_swap_b32_e32 v204, v206
	v_permlane32_swap_b32_e32 v205, v207
	v_permlane32_swap_b32_e32 v208, v210
	v_permlane32_swap_b32_e32 v209, v211
	s_lshl_b64 s[4:5], s[66:67], 11
	s_add_u32 s4, s4, s80
	s_addc_u32 s5, s5, s81
	s_lshl_b32 s53, s68, 7
	s_add_u32 s4, s4, s53
	s_addc_u32 s5, s5, 0
	v_lshlrev_b32_e32 v234, 11, v140
	v_lshl_or_b32 v234, v141, 4, v234
	global_store_dwordx4 v234, v[196:199], s[4:5] sc1
	global_store_dwordx4 v234, v[200:203], s[4:5] offset:32 sc1
	global_store_dwordx4 v234, v[204:207], s[4:5] offset:64 sc1
	global_store_dwordx4 v234, v[208:211], s[4:5] offset:96 sc1
	v_lshlrev_b32_e32 v230, 16, v196
	v_and_b32_e32 v231, 0xffff0000, v196
	v_fmac_f32_e32 v213, v230, v230
	v_fmac_f32_e32 v213, v231, v231
	v_lshlrev_b32_e32 v230, 16, v197
	v_and_b32_e32 v231, 0xffff0000, v197
	v_fmac_f32_e32 v213, v230, v230
	v_fmac_f32_e32 v213, v231, v231
	v_lshlrev_b32_e32 v230, 16, v198
	v_and_b32_e32 v231, 0xffff0000, v198
	v_fmac_f32_e32 v213, v230, v230
	v_fmac_f32_e32 v213, v231, v231
	v_lshlrev_b32_e32 v230, 16, v199
	v_and_b32_e32 v231, 0xffff0000, v199
	v_fmac_f32_e32 v213, v230, v230
	v_fmac_f32_e32 v213, v231, v231
	v_lshlrev_b32_e32 v230, 16, v200
	v_and_b32_e32 v231, 0xffff0000, v200
	v_fmac_f32_e32 v213, v230, v230
	v_fmac_f32_e32 v213, v231, v231
	v_lshlrev_b32_e32 v230, 16, v201
	v_and_b32_e32 v231, 0xffff0000, v201
	v_fmac_f32_e32 v213, v230, v230
	v_fmac_f32_e32 v213, v231, v231
	v_lshlrev_b32_e32 v230, 16, v202
	v_and_b32_e32 v231, 0xffff0000, v202
	v_fmac_f32_e32 v213, v230, v230
	v_fmac_f32_e32 v213, v231, v231
	v_lshlrev_b32_e32 v230, 16, v203
	v_and_b32_e32 v231, 0xffff0000, v203
	v_fmac_f32_e32 v213, v230, v230
	v_fmac_f32_e32 v213, v231, v231
	v_lshlrev_b32_e32 v230, 16, v204
	v_and_b32_e32 v231, 0xffff0000, v204
	v_fmac_f32_e32 v213, v230, v230
	v_fmac_f32_e32 v213, v231, v231
	v_lshlrev_b32_e32 v230, 16, v205
	v_and_b32_e32 v231, 0xffff0000, v205
	v_fmac_f32_e32 v213, v230, v230
	v_fmac_f32_e32 v213, v231, v231
	v_lshlrev_b32_e32 v230, 16, v206
	v_and_b32_e32 v231, 0xffff0000, v206
	v_fmac_f32_e32 v213, v230, v230
	v_fmac_f32_e32 v213, v231, v231
	v_lshlrev_b32_e32 v230, 16, v207
	v_and_b32_e32 v231, 0xffff0000, v207
	v_fmac_f32_e32 v213, v230, v230
	v_fmac_f32_e32 v213, v231, v231
	v_lshlrev_b32_e32 v230, 16, v208
	v_and_b32_e32 v231, 0xffff0000, v208
	v_fmac_f32_e32 v213, v230, v230
	v_fmac_f32_e32 v213, v231, v231
	v_lshlrev_b32_e32 v230, 16, v209
	v_and_b32_e32 v231, 0xffff0000, v209
	v_fmac_f32_e32 v213, v230, v230
	v_fmac_f32_e32 v213, v231, v231
	v_lshlrev_b32_e32 v230, 16, v210
	v_and_b32_e32 v231, 0xffff0000, v210
	v_fmac_f32_e32 v213, v230, v230
	v_fmac_f32_e32 v213, v231, v231
	v_lshlrev_b32_e32 v230, 16, v211
	v_and_b32_e32 v231, 0xffff0000, v211
	v_fmac_f32_e32 v213, v230, v230
	v_fmac_f32_e32 v213, v231, v231
	v_mov_b32_e32 v230, v213
	s_nop 1
	v_permlane32_swap_b32_e32 v213, v230
	s_nop 0
	v_add_f32_e32 v213, v213, v230
	s_lshl_b64 s[4:5], s[66:67], 5
	s_add_u32 s4, s4, s82
	s_addc_u32 s5, s5, s83
	s_lshl_b32 s53, s68, 2
	s_add_u32 s4, s4, s53
	s_addc_u32 s5, s5, 0
	v_lshlrev_b32_e32 v235, 5, v140
	v_cmp_gt_u32_e32 vcc, 32, v139
	s_and_saveexec_b64 s[46:47], vcc
	global_store_dword v235, v213, s[4:5]
	s_or_b64 exec, exec, s[46:47]
	s_mov_b32 m0, s54
	s_lshl_b32 s48, s68, 7
	s_xor_b64 s[46:47], s[70:71], -1
	s_branch .LBB0_915

; #define LAS __attribute__((address_space(3)))
; __device__ __forceinline__ int crow(int r, int hi) { return (r & 3) + 8 * (r >> 2) + 4 * hi; }
; __device__ __forceinline__ unsigned cvtpk_s(float lo, float hi) { f32x2 v = {lo, hi}; typedef __bf16 bf16x2_t __attribute__((ext_vector_type(2))); bf16x2_t b = __builtin_convertvector(v, bf16x2_t); return __builtin_bit_cast(unsigned, b); }
; __device__ __forceinline__ void attn_unit(int b, int h, int qb, const bf16* Q, const bf16* __restrict__ Kn, const bf16* __restrict__ Kpe, const bf16* __restrict__ V, bf16* O, float* ASS, LAS char* shm) {
;     ...
;     { auto rr = __builtin_amdgcn_permlane32_swap(__float_as_uint(l_run), __float_as_uint(l_run), false, false); l_run = __uint_as_float(rr[0]) + __uint_as_float(rr[1]); }
;     if (hi == 0) wsf[32 + r32] = l_run; asm volatile("s_waitcnt lgkmcnt(0)" ::: "memory");
;     float rli[16];
; #pragma unroll
;     for (int r = 0; r < 16; ++r) rli[r] = __builtin_amdgcn_rcpf(wsf[32 + crow(r, hi)]);
;     bf16* Ow = O + (rowbase + q0 + wid * QBLK) * OP + h * 64;
;     { LAS unsigned short* stg = (LAS unsigned short*)(shm + LDS_OST) + wid * 2048;
; #pragma unroll
;       for (int r = 0; r < 16; ++r) { const int orow = crow(r, hi);
; #pragma unroll
;           for (int d0 = 0; d0 < 2; ++d0) stg[orow * 64 + d0 * 32 + r32] = (unsigned short)(cvtpk_s(o[d0][r] * rli[r], 0.f) & 0xffffu); }
;       asm volatile("s_waitcnt lgkmcnt(0)" ::: "memory");
; #pragma unroll
;       for (int i = 0; i < 4; ++i) { const int row = i * 8 + (lane >> 3), ch = lane & 7; const u32x4 v = *(const LAS u32x4*)(stg + row * 64 + ch * 8); *(u32x4*)(Ow + (long)row * OP + ch * 8) = v;
;           float sq = 0.f;
; #pragma unroll
;           for (int k = 0; k < 4; ++k) { const float a = __uint_as_float(v[k] << 16), bq = __uint_as_float(v[k] & 0xffff0000u); sq += a * a + bq * bq; }
;           sq += __shfl_xor(sq, 1); sq += __shfl_xor(sq, 2); sq += __shfl_xor(sq, 4);
;           if (ch == 0) ASS[(rowbase + q0 + wid * QBLK + row) * 8 + h] = sq; } }
.Lat_u2t_skip:
	s_nop 7
	s_nop 7
	v_mov_b32_e32 v212, v128
	s_nop 1
	v_permlane32_swap_b32_e32 v128, v212
	s_nop 0
	v_add_f32_e32 v128, v128, v212
	v_rcp_f32_e32 v212, v128
	v_mov_b32_e32 v213, 0
	v_mul_f32_e32 v230, v18, v212
	v_mul_f32_e32 v231, v19, v212
	v_mul_f32_e32 v232, v20, v212
	v_mul_f32_e32 v233, v21, v212
	v_cvt_pk_bf16_f32 v196, v230, v231
	v_cvt_pk_bf16_f32 v197, v232, v233
	v_mul_f32_e32 v230, v22, v212
	v_mul_f32_e32 v231, v23, v212
	v_mul_f32_e32 v232, v24, v212
	v_mul_f32_e32 v233, v25, v212
	v_cvt_pk_bf16_f32 v198, v230, v231
	v_cvt_pk_bf16_f32 v199, v232, v233
	v_mul_f32_e32 v230, v26, v212
	v_mul_f32_e32 v231, v27, v212
	v_mul_f32_e32 v232, v28, v212
	v_mul_f32_e32 v233, v29, v212
	v_cvt_pk_bf16_f32 v200, v230, v231
	v_cvt_pk_bf16_f32 v201, v232, v233
	v_mul_f32_e32 v230, v30, v212
	v_mul_f32_e32 v231, v31, v212
	v_mul_f32_e32 v232, v32, v212
	v_mul_f32_e32 v233, v33, v212
	v_cvt_pk_bf16_f32 v202, v230, v231
	v_cvt_pk_bf16_f32 v203, v232, v233
	v_mul_f32_e32 v230, v2, v212
	v_mul_f32_e32 v231, v3, v212
	v_mul_f32_e32 v232, v4, v212
	v_mul_f32_e32 v233, v5, v212
	v_cvt_pk_bf16_f32 v204, v230, v231
	v_cvt_pk_bf16_f32 v205, v232, v233
	v_mul_f32_e32 v230, v6, v212
	v_mul_f32_e32 v231, v7, v212
	v_mul_f32_e32 v232, v8, v212
	v_mul_f32_e32 v233, v9, v212
	v_cvt_pk_bf16_f32 v206, v230, v231
	v_cvt_pk_bf16_f32 v207, v232, v233
	v_mul_f32_e32 v230, v10, v212
	v_mul_f32_e32 v231, v11, v212
	v_mul_f32_e32 v232, v12, v212
	v_mul_f32_e32 v233, v13, v212
	v_cvt_pk_bf16_f32 v208, v230, v231
	v_cvt_pk_bf16_f32 v209, v232, v233
	v_mul_f32_e32 v230, v14, v212
	v_mul_f32_e32 v231, v15, v212
	v_mul_f32_e32 v232, v16, v212
	v_mul_f32_e32 v233, v17, v212
	v_cvt_pk_bf16_f32 v210, v230, v231
	v_cvt_pk_bf16_f32 v211, v232, v233
	s_nop 1
	v_permlane32_swap_b32_e32 v196, v198
	v_permlane32_swap_b32_e32 v197, v199
	v_permlane32_swap_b32_e32 v200, v202
	v_permlane32_swap_b32_e32 v201, v203
	v_permlane32_swap_b32_e32 v204, v206
	v_permlane32_swap_b32_e32 v205, v207
	v_permlane32_swap_b32_e32 v208, v210
	v_permlane32_swap_b32_e32 v209, v211
	s_lshl_b64 s[4:5], s[52:53], 11
	s_add_u32 s4, s4, s80
	s_addc_u32 s5, s5, s81
	s_lshl_b32 s63, s68, 7
	s_add_u32 s4, s4, s63
	s_addc_u32 s5, s5, 0
	v_lshlrev_b32_e32 v234, 11, v141
	v_lshl_or_b32 v234, v142, 4, v234
	global_store_dwordx4 v234, v[196:199], s[4:5] sc1
	global_store_dwordx4 v234, v[200:203], s[4:5] offset:32 sc1
	global_store_dwordx4 v234, v[204:207], s[4:5] offset:64 sc1
	global_store_dwordx4 v234, v[208:211], s[4:5] offset:96 sc1
	v_lshlrev_b32_e32 v230, 16, v196
	v_and_b32_e32 v231, 0xffff0000, v196
	v_fmac_f32_e32 v213, v230, v230
	v_fmac_f32_e32 v213, v231, v231
	v_lshlrev_b32_e32 v230, 16, v197
	v_and_b32_e32 v231, 0xffff0000, v197
	v_fmac_f32_e32 v213, v230, v230
	v_fmac_f32_e32 v213, v231, v231
	v_lshlrev_b32_e32 v230, 16, v198
	v_and_b32_e32 v231, 0xffff0000, v198
	v_fmac_f32_e32 v213, v230, v230
	v_fmac_f32_e32 v213, v231, v231
	v_lshlrev_b32_e32 v230, 16, v199
	v_and_b32_e32 v231, 0xffff0000, v199
	v_fmac_f32_e32 v213, v230, v230
	v_fmac_f32_e32 v213, v231, v231
	v_lshlrev_b32_e32 v230, 16, v200
	v_and_b32_e32 v231, 0xffff0000, v200
	v_fmac_f32_e32 v213, v230, v230
	v_fmac_f32_e32 v213, v231, v231
	v_lshlrev_b32_e32 v230, 16, v201
	v_and_b32_e32 v231, 0xffff0000, v201
	v_fmac_f32_e32 v213, v230, v230
	v_fmac_f32_e32 v213, v231, v231
	v_lshlrev_b32_e32 v230, 16, v202
	v_and_b32_e32 v231, 0xffff0000, v202
	v_fmac_f32_e32 v213, v230, v230
	v_fmac_f32_e32 v213, v231, v231
	v_lshlrev_b32_e32 v230, 16, v203
	v_and_b32_e32 v231, 0xffff0000, v203
	v_fmac_f32_e32 v213, v230, v230
	v_fmac_f32_e32 v213, v231, v231
	v_lshlrev_b32_e32 v230, 16, v204
	v_and_b32_e32 v231, 0xffff0000, v204
	v_fmac_f32_e32 v213, v230, v230
	v_fmac_f32_e32 v213, v231, v231
	v_lshlrev_b32_e32 v230, 16, v205
	v_and_b32_e32 v231, 0xffff0000, v205
	v_fmac_f32_e32 v213, v230, v230
	v_fmac_f32_e32 v213, v231, v231
	v_lshlrev_b32_e32 v230, 16, v206
	v_and_b32_e32 v231, 0xffff0000, v206
	v_fmac_f32_e32 v213, v230, v230
	v_fmac_f32_e32 v213, v231, v231
	v_lshlrev_b32_e32 v230, 16, v207
	v_and_b32_e32 v231, 0xffff0000, v207
	v_fmac_f32_e32 v213, v230, v230
	v_fmac_f32_e32 v213, v231, v231
	v_lshlrev_b32_e32 v230, 16, v208
	v_and_b32_e32 v231, 0xffff0000, v208
	v_fmac_f32_e32 v213, v230, v230
	v_fmac_f32_e32 v213, v231, v231
	v_lshlrev_b32_e32 v230, 16, v209
	v_and_b32_e32 v231, 0xffff0000, v209
	v_fmac_f32_e32 v213, v230, v230
	v_fmac_f32_e32 v213, v231, v231
	v_lshlrev_b32_e32 v230, 16, v210
	v_and_b32_e32 v231, 0xffff0000, v210
	v_fmac_f32_e32 v213, v230, v230
	v_fmac_f32_e32 v213, v231, v231
	v_lshlrev_b32_e32 v230, 16, v211
	v_and_b32_e32 v231, 0xffff0000, v211
	v_fmac_f32_e32 v213, v230, v230
	v_fmac_f32_e32 v213, v231, v231
	v_mov_b32_e32 v230, v213
	s_nop 1
	v_permlane32_swap_b32_e32 v213, v230
	s_nop 0
	v_add_f32_e32 v213, v213, v230
	s_lshl_b64 s[4:5], s[52:53], 5
	s_add_u32 s4, s4, s82
	s_addc_u32 s5, s5, s83
	s_lshl_b32 s63, s68, 2
	s_add_u32 s4, s4, s63
	s_addc_u32 s5, s5, 0
	v_lshlrev_b32_e32 v235, 5, v141
	v_cmp_gt_u32_e32 vcc, 32, v140
	s_and_saveexec_b64 s[54:55], vcc
	global_store_dword v235, v213, s[4:5]
	s_or_b64 exec, exec, s[54:55]
	s_mov_b32 m0, s65
	s_branch .LBB0_869
